# compute segments now start with the MFMAs right after the barrier: no s_setprio and no redundant lgkmcnt(0) in the K loop
# speedup vs baseline: 1.0074x; 1.0063x over previous
; #define PG8_STAGE(bufoff, gbase, voff) do { _Pragma("unroll") for (int _i = 0; _i < 2; ++_i) \
;         __builtin_amdgcn_global_load_lds((const unsigned*)((const char*)(gbase) + (voff)[_i]), (PG8_LAS unsigned*)(lds + (bufoff) + ldsw + _i * 8192), 16, 0, 0); } while (0)
; #define PG8_LDA(dst, b, h) do { _Pragma("unroll") for (int m = 0; m < 4; ++m) _Pragma("unroll") for (int k = 0; k < 2; ++k) dst[m][k] = *(const PG8_LAS bf16x8*)(lds + PG8_SA(b, h) + aoff + m * 2048 + k * 1024); } while (0)
; #define PG8_LDB(dst, b, h) do { _Pragma("unroll") for (int n = 0; n < 2; ++n) _Pragma("unroll") for (int k = 0; k < 2; ++k) dst[n][k] = *(const PG8_LAS bf16x8*)(lds + PG8_SB(b, h) + boff + n * 2048 + k * 1024); } while (0)
; #define PG8_WAIT_V(n) asm volatile("s_waitcnt vmcnt(" #n ")" ::: "memory")
; #define PG8_WAIT_L(n) asm volatile("s_waitcnt lgkmcnt(" #n ")" ::: "memory")
; #define PG8_BAR __builtin_amdgcn_s_barrier()
; #define PG8_SCHED __builtin_amdgcn_sched_barrier(0)
; template <class Epi, class Sched, bool ALIGN_EPI = false, bool SP2 = false>
; __device__ __forceinline__ void gemm_phase(PG8_LAS unsigned char* lds, const Gemm g, const Sched& S, const Epi& E) {
;     ...
;         const char* nA = has_next ? (const char*)g.A + (size_t)nxt.pm * tstep : cA; const char* nB = has_next ? (const char*)g.Bt + (size_t)nxt.pn * tstep : cB;
;         for (int t = 0; t < nt; t += 2) {
;             const bool last = (t == nt - 2);
;             const char* a1 = cA + (size_t)(t + 1) * kstep;
;             const char* a2 = last ? nA : cA + (size_t)(t + 2) * kstep; const char* b2 = last ? nB : cB + (size_t)(t + 2) * kstep;
;             const char* a3 = a2 + kstep; const char* b3 = b2 + kstep;
;             if (last && has_next) S.a_ready(nxt);
;             if constexpr (SP2) {
;             PG8_LDB(B0, 0, 0); PG8_LDB(B1, 0, 1); PG8_SCHED; PG8_LDA(At, 0, 0); PG8_STAGE(PG8_SA(1, 1), a1 + hstep, voffA);
;             PG8_WAIT_V(8); PG8_WAIT_L(0); PG8_BAR; PG8_MMA(0, 0, At, B0); PG8_MMA(0, 1, At, B1); PG8_BAR; PG8_SCHED;
;             PG8_LDA(At, 0, 1); PG8_STAGE(PG8_SB(0, 0), b2, voffB); PG8_STAGE(PG8_SB(0, 1), b2 + hstep, voffB); PG8_STAGE(PG8_SA(0, 0), a2, voffA);
;             PG8_WAIT_V(8); PG8_WAIT_L(0); PG8_BAR; PG8_MMA(1, 0, At, B0); PG8_MMA(1, 1, At, B1); PG8_BAR; PG8_SCHED;
.LBB0_321:
	s_add_u32 s12, s16, 0x80
	s_addc_u32 s13, s17, 0
	s_add_u32 s16, s14, 0x100
	s_addc_u32 s17, s15, 0
	s_mov_b32 s14, 0
	s_nop 0
	s_nop 0
	s_waitcnt lgkmcnt(0)
	s_add_i32 s42, s14, 2
	s_add_u32 s43, s12, 0x80
	s_addc_u32 s15, s13, 0
	s_add_i32 s75, 0, 0x10000
	s_cmp_eq_u32 s25, s14
	s_cselect_b32 s15, s55, s15
	s_cselect_b32 s14, s54, s43
	s_cselect_b32 vcc_hi, s65, s17
	s_cselect_b32 vcc_lo, s64, s16
	s_add_i32 s43, 0, 0x14000
	v_add_u32_e32 v142, s75, v199
	v_add_u32_e32 v178, s43, v199
	ds_read_b128 v[130:133], v142
	ds_read_b128 v[134:137], v142 offset:1024
	ds_read_b128 v[138:141], v142 offset:2048
	ds_read_b128 v[142:145], v142 offset:3072
	ds_read_b128 v[170:173], v178
	ds_read_b128 v[174:177], v178 offset:1024
	ds_read_b128 v[202:205], v178 offset:2048
	ds_read_b128 v[206:209], v178 offset:3072
	v_lshl_add_u64 v[178:179], s[12:13], 0, v[166:167]
	s_add_i32 m0, s56, 0xc000
	ds_read_b128 v[210:213], v201
	ds_read_b128 v[214:217], v201 offset:1024
	ds_read_b128 v[218:221], v201 offset:2048
	ds_read_b128 v[222:225], v201 offset:3072
	ds_read_b128 v[226:229], v201 offset:4096
	ds_read_b128 v[230:233], v201 offset:5120
	ds_read_b128 v[234:237], v201 offset:6144
	ds_read_b128 v[238:241], v201 offset:7168
	global_load_lds_dwordx4 v[178:179], off
	v_lshl_add_u64 v[178:179], s[12:13], 0, v[168:169]
	s_add_i32 m0, s56, 0xe000
	s_nop 0
	global_load_lds_dwordx4 v[178:179], off
	s_waitcnt vmcnt(8)
	s_waitcnt lgkmcnt(0)
	s_barrier
	v_mfma_f32_16x16x32_bf16 v[126:129], v[130:133], v[210:213], 0
	v_mfma_f32_16x16x32_bf16 v[126:129], v[134:137], v[214:217], v[126:129]
	v_mfma_f32_16x16x32_bf16 v[122:125], v[138:141], v[210:213], 0
	v_mfma_f32_16x16x32_bf16 v[122:125], v[142:145], v[214:217], v[122:125]
	v_mfma_f32_16x16x32_bf16 v[110:113], v[130:133], v[218:221], 0
	v_mfma_f32_16x16x32_bf16 v[110:113], v[134:137], v[222:225], v[110:113]
	v_mfma_f32_16x16x32_bf16 v[106:109], v[138:141], v[218:221], 0
	v_mfma_f32_16x16x32_bf16 v[106:109], v[142:145], v[222:225], v[106:109]
	v_mfma_f32_16x16x32_bf16 v[94:97], v[130:133], v[226:229], 0
	v_mfma_f32_16x16x32_bf16 v[94:97], v[134:137], v[230:233], v[94:97]
	v_mfma_f32_16x16x32_bf16 v[90:93], v[138:141], v[226:229], 0
	v_mfma_f32_16x16x32_bf16 v[90:93], v[142:145], v[230:233], v[90:93]
	v_mfma_f32_16x16x32_bf16 v[78:81], v[130:133], v[234:237], 0
	v_mfma_f32_16x16x32_bf16 v[78:81], v[134:137], v[238:241], v[78:81]
	v_mfma_f32_16x16x32_bf16 v[74:77], v[138:141], v[234:237], 0
	v_mfma_f32_16x16x32_bf16 v[74:77], v[142:145], v[238:241], v[74:77]
	v_mfma_f32_16x16x32_bf16 v[118:121], v[170:173], v[210:213], 0
	v_mfma_f32_16x16x32_bf16 v[118:121], v[174:177], v[214:217], v[118:121]
	v_mfma_f32_16x16x32_bf16 v[114:117], v[202:205], v[210:213], 0
	v_mfma_f32_16x16x32_bf16 v[114:117], v[206:209], v[214:217], v[114:117]
	v_mfma_f32_16x16x32_bf16 v[102:105], v[170:173], v[218:221], 0
	v_mfma_f32_16x16x32_bf16 v[102:105], v[174:177], v[222:225], v[102:105]
	v_mfma_f32_16x16x32_bf16 v[98:101], v[202:205], v[218:221], 0
	v_mfma_f32_16x16x32_bf16 v[98:101], v[206:209], v[222:225], v[98:101]
	v_mfma_f32_16x16x32_bf16 v[86:89], v[170:173], v[226:229], 0
	v_mfma_f32_16x16x32_bf16 v[86:89], v[174:177], v[230:233], v[86:89]
	v_mfma_f32_16x16x32_bf16 v[82:85], v[202:205], v[226:229], 0
	v_mfma_f32_16x16x32_bf16 v[82:85], v[206:209], v[230:233], v[82:85]
	v_mfma_f32_16x16x32_bf16 v[70:73], v[170:173], v[234:237], 0
	v_mfma_f32_16x16x32_bf16 v[70:73], v[174:177], v[238:241], v[70:73]
	v_mfma_f32_16x16x32_bf16 v[66:69], v[202:205], v[234:237], 0
	v_mfma_f32_16x16x32_bf16 v[66:69], v[206:209], v[238:241], v[66:69]
	s_barrier
	s_add_i32 s75, s75, s23
	v_lshl_add_u64 v[178:179], vcc, 0, v[0:1]
	s_mov_b32 m0, s75
	ds_read_b128 v[210:213], v201 offset:16384
	ds_read_b128 v[214:217], v201 offset:17408
	ds_read_b128 v[218:221], v201 offset:18432
	ds_read_b128 v[222:225], v201 offset:19456
	ds_read_b128 v[226:229], v201 offset:20480
	ds_read_b128 v[230:233], v201 offset:21504
	ds_read_b128 v[234:237], v201 offset:22528
	ds_read_b128 v[238:241], v201 offset:23552
	global_load_lds_dwordx4 v[178:179], off
	s_add_i32 m0, s75, 0x2000
	v_lshl_add_u64 v[242:243], vcc, 0, v[162:163]
	s_add_u32 vcc_lo, vcc_lo, s84
	s_addc_u32 vcc_hi, vcc_hi, 0
	s_add_i32 s43, s43, s23
	global_load_lds_dwordx4 v[242:243], off
	v_lshl_add_u64 v[244:245], vcc, 0, v[0:1]
	s_mov_b32 m0, s43
	v_lshl_add_u64 v[246:247], vcc, 0, v[162:163]
	global_load_lds_dwordx4 v[244:245], off
	s_add_i32 m0, s43, 0x2000
	v_lshl_add_u64 v[248:249], s[14:15], 0, v[158:159]
	global_load_lds_dwordx4 v[246:247], off
	s_mov_b32 m0, s56
	v_lshl_add_u64 v[250:251], s[14:15], 0, v[160:161]
	global_load_lds_dwordx4 v[248:249], off
	s_mov_b32 m0, s82
	s_nop 0
	global_load_lds_dwordx4 v[250:251], off
	s_waitcnt vmcnt(8)
	s_waitcnt lgkmcnt(0)
	s_barrier
; #define PG8_STAGE(bufoff, gbase, voff) do { _Pragma("unroll") for (int _i = 0; _i < 2; ++_i) \
;         __builtin_amdgcn_global_load_lds((const unsigned*)((const char*)(gbase) + (voff)[_i]), (PG8_LAS unsigned*)(lds + (bufoff) + ldsw + _i * 8192), 16, 0, 0); } while (0)
; #define PG8_LDA(dst, b, h) do { _Pragma("unroll") for (int m = 0; m < 4; ++m) _Pragma("unroll") for (int k = 0; k < 2; ++k) dst[m][k] = *(const PG8_LAS bf16x8*)(lds + PG8_SA(b, h) + aoff + m * 2048 + k * 1024); } while (0)
; #define PG8_LDB(dst, b, h) do { _Pragma("unroll") for (int n = 0; n < 2; ++n) _Pragma("unroll") for (int k = 0; k < 2; ++k) dst[n][k] = *(const PG8_LAS bf16x8*)(lds + PG8_SB(b, h) + boff + n * 2048 + k * 1024); } while (0)
; #define PG8_MMA(ai, bj, At, Bt) do { __builtin_amdgcn_s_setprio(1); _Pragma("unroll") for (int m = 0; m < 4; ++m) _Pragma("unroll") for (int n = 0; n < 2; ++n) _Pragma("unroll") for (int k = 0; k < 2; ++k) \
;         acc[ai][bj][m][n] = __builtin_amdgcn_mfma_f32_16x16x32_bf16(Bt[n][k], At[m][k], acc[ai][bj][m][n], 0, 0, 0); __builtin_amdgcn_s_setprio(0); } while (0)
; #define PG8_WAIT_V(n) asm volatile("s_waitcnt vmcnt(" #n ")" ::: "memory")
; #define PG8_WAIT_L(n) asm volatile("s_waitcnt lgkmcnt(" #n ")" ::: "memory")
; #define PG8_BAR __builtin_amdgcn_s_barrier()
; #define PG8_SCHED __builtin_amdgcn_sched_barrier(0)
; template <class Epi, class Sched, bool ALIGN_EPI = false, bool SP2 = false>
; __device__ __forceinline__ void gemm_phase(PG8_LAS unsigned char* lds, const Gemm g, const Sched& S, const Epi& E) {
;     ...
;             PG8_WAIT_V(8); PG8_WAIT_L(0); PG8_BAR; PG8_MMA(1, 0, At, B0); PG8_MMA(1, 1, At, B1); PG8_BAR; PG8_SCHED;
;             PG8_LDB(B0, 1, 0); PG8_LDB(B1, 1, 1); PG8_SCHED; PG8_LDA(At, 1, 0); PG8_STAGE(PG8_SA(0, 1), a2 + hstep, voffA);
;             PG8_WAIT_V(8); PG8_WAIT_L(0); PG8_BAR; PG8_MMA(0, 0, At, B0); PG8_MMA(0, 1, At, B1); PG8_BAR; PG8_SCHED;
	v_mfma_f32_16x16x32_bf16 v[62:65], v[130:133], v[210:213], 0
	v_mfma_f32_16x16x32_bf16 v[62:65], v[134:137], v[214:217], v[62:65]
	v_mfma_f32_16x16x32_bf16 v[58:61], v[138:141], v[210:213], 0
	v_mfma_f32_16x16x32_bf16 v[58:61], v[142:145], v[214:217], v[58:61]
	v_mfma_f32_16x16x32_bf16 v[46:49], v[130:133], v[218:221], 0
	v_mfma_f32_16x16x32_bf16 v[46:49], v[134:137], v[222:225], v[46:49]
	v_mfma_f32_16x16x32_bf16 v[42:45], v[138:141], v[218:221], 0
	v_mfma_f32_16x16x32_bf16 v[42:45], v[142:145], v[222:225], v[42:45]
	v_mfma_f32_16x16x32_bf16 v[30:33], v[130:133], v[226:229], 0
	v_mfma_f32_16x16x32_bf16 v[30:33], v[134:137], v[230:233], v[30:33]
	v_mfma_f32_16x16x32_bf16 v[26:29], v[138:141], v[226:229], 0
	v_mfma_f32_16x16x32_bf16 v[26:29], v[142:145], v[230:233], v[26:29]
	v_mfma_f32_16x16x32_bf16 v[14:17], v[130:133], v[234:237], 0
	v_mfma_f32_16x16x32_bf16 v[14:17], v[134:137], v[238:241], v[14:17]
	v_mfma_f32_16x16x32_bf16 v[10:13], v[138:141], v[234:237], 0
	v_mfma_f32_16x16x32_bf16 v[10:13], v[142:145], v[238:241], v[10:13]
	v_mfma_f32_16x16x32_bf16 v[54:57], v[170:173], v[210:213], 0
	v_mfma_f32_16x16x32_bf16 v[54:57], v[174:177], v[214:217], v[54:57]
	v_mfma_f32_16x16x32_bf16 v[50:53], v[202:205], v[210:213], 0
	v_mfma_f32_16x16x32_bf16 v[50:53], v[206:209], v[214:217], v[50:53]
	v_mfma_f32_16x16x32_bf16 v[38:41], v[170:173], v[218:221], 0
	v_mfma_f32_16x16x32_bf16 v[38:41], v[174:177], v[222:225], v[38:41]
	v_mfma_f32_16x16x32_bf16 v[34:37], v[202:205], v[218:221], 0
	v_mfma_f32_16x16x32_bf16 v[34:37], v[206:209], v[222:225], v[34:37]
	v_mfma_f32_16x16x32_bf16 v[22:25], v[170:173], v[226:229], 0
	v_mfma_f32_16x16x32_bf16 v[22:25], v[174:177], v[230:233], v[22:25]
	v_mfma_f32_16x16x32_bf16 v[18:21], v[202:205], v[226:229], 0
	v_mfma_f32_16x16x32_bf16 v[18:21], v[206:209], v[230:233], v[18:21]
	v_mfma_f32_16x16x32_bf16 v[6:9], v[170:173], v[234:237], 0
	v_mfma_f32_16x16x32_bf16 v[6:9], v[174:177], v[238:241], v[6:9]
	v_mfma_f32_16x16x32_bf16 v[2:5], v[202:205], v[234:237], 0
	v_mfma_f32_16x16x32_bf16 v[2:5], v[206:209], v[238:241], v[2:5]
	s_barrier
	s_add_i32 s43, 0, 0x18000
	s_add_i32 s75, 0, 0x1c000
	v_add_u32_e32 v142, s43, v199
	v_add_u32_e32 v206, s75, v199
	ds_read_b128 v[130:133], v142
	ds_read_b128 v[134:137], v142 offset:1024
	ds_read_b128 v[138:141], v142 offset:2048
	ds_read_b128 v[142:145], v142 offset:3072
	ds_read_b128 v[170:173], v206
	ds_read_b128 v[174:177], v206 offset:1024
	ds_read_b128 v[202:205], v206 offset:2048
	ds_read_b128 v[206:209], v206 offset:3072
	s_add_u32 s14, s14, s84
	s_addc_u32 s15, s15, 0
	s_mov_b32 m0, s83
	v_lshl_add_u64 v[252:253], s[14:15], 0, v[158:159]
	ds_read_b128 v[210:213], v201 offset:32768
	ds_read_b128 v[214:217], v201 offset:33792
	ds_read_b128 v[218:221], v201 offset:34816
	ds_read_b128 v[222:225], v201 offset:35840
	ds_read_b128 v[226:229], v201 offset:36864
	ds_read_b128 v[230:233], v201 offset:37888
	ds_read_b128 v[234:237], v201 offset:38912
	ds_read_b128 v[238:241], v201 offset:39936
	global_load_lds_dwordx4 v[252:253], off
	v_lshl_add_u64 v[252:253], s[14:15], 0, v[160:161]
	s_mov_b32 m0, s24
	s_nop 0
	global_load_lds_dwordx4 v[252:253], off
	s_waitcnt vmcnt(8)
	s_waitcnt lgkmcnt(0)
	s_barrier
	v_mfma_f32_16x16x32_bf16 v[126:129], v[130:133], v[210:213], v[126:129]
	v_mfma_f32_16x16x32_bf16 v[126:129], v[134:137], v[214:217], v[126:129]
	v_mfma_f32_16x16x32_bf16 v[122:125], v[138:141], v[210:213], v[122:125]
	v_mfma_f32_16x16x32_bf16 v[122:125], v[142:145], v[214:217], v[122:125]
	v_mfma_f32_16x16x32_bf16 v[110:113], v[130:133], v[218:221], v[110:113]
	v_mfma_f32_16x16x32_bf16 v[110:113], v[134:137], v[222:225], v[110:113]
	v_mfma_f32_16x16x32_bf16 v[106:109], v[138:141], v[218:221], v[106:109]
	v_mfma_f32_16x16x32_bf16 v[106:109], v[142:145], v[222:225], v[106:109]
	v_mfma_f32_16x16x32_bf16 v[94:97], v[130:133], v[226:229], v[94:97]
	v_mfma_f32_16x16x32_bf16 v[94:97], v[134:137], v[230:233], v[94:97]
	v_mfma_f32_16x16x32_bf16 v[90:93], v[138:141], v[226:229], v[90:93]
	v_mfma_f32_16x16x32_bf16 v[90:93], v[142:145], v[230:233], v[90:93]
	v_mfma_f32_16x16x32_bf16 v[78:81], v[130:133], v[234:237], v[78:81]
	v_mfma_f32_16x16x32_bf16 v[78:81], v[134:137], v[238:241], v[78:81]
	v_mfma_f32_16x16x32_bf16 v[74:77], v[138:141], v[234:237], v[74:77]
	v_mfma_f32_16x16x32_bf16 v[74:77], v[142:145], v[238:241], v[74:77]
	v_mfma_f32_16x16x32_bf16 v[118:121], v[170:173], v[210:213], v[118:121]
	v_mfma_f32_16x16x32_bf16 v[118:121], v[174:177], v[214:217], v[118:121]
	v_mfma_f32_16x16x32_bf16 v[114:117], v[202:205], v[210:213], v[114:117]
	v_mfma_f32_16x16x32_bf16 v[114:117], v[206:209], v[214:217], v[114:117]
	v_mfma_f32_16x16x32_bf16 v[102:105], v[170:173], v[218:221], v[102:105]
	v_mfma_f32_16x16x32_bf16 v[102:105], v[174:177], v[222:225], v[102:105]
	v_mfma_f32_16x16x32_bf16 v[98:101], v[202:205], v[218:221], v[98:101]
	v_mfma_f32_16x16x32_bf16 v[98:101], v[206:209], v[222:225], v[98:101]
	v_mfma_f32_16x16x32_bf16 v[86:89], v[170:173], v[226:229], v[86:89]
	v_mfma_f32_16x16x32_bf16 v[86:89], v[174:177], v[230:233], v[86:89]
	v_mfma_f32_16x16x32_bf16 v[82:85], v[202:205], v[226:229], v[82:85]
	v_mfma_f32_16x16x32_bf16 v[82:85], v[206:209], v[230:233], v[82:85]
	v_mfma_f32_16x16x32_bf16 v[70:73], v[170:173], v[234:237], v[70:73]
	v_mfma_f32_16x16x32_bf16 v[70:73], v[174:177], v[238:241], v[70:73]
	v_mfma_f32_16x16x32_bf16 v[66:69], v[202:205], v[234:237], v[66:69]
	v_mfma_f32_16x16x32_bf16 v[66:69], v[206:209], v[238:241], v[66:69]
	s_barrier
; #define PG8_STAGE(bufoff, gbase, voff) do { _Pragma("unroll") for (int _i = 0; _i < 2; ++_i) \
;         __builtin_amdgcn_global_load_lds((const unsigned*)((const char*)(gbase) + (voff)[_i]), (PG8_LAS unsigned*)(lds + (bufoff) + ldsw + _i * 8192), 16, 0, 0); } while (0)
; #define PG8_LDA(dst, b, h) do { _Pragma("unroll") for (int m = 0; m < 4; ++m) _Pragma("unroll") for (int k = 0; k < 2; ++k) dst[m][k] = *(const PG8_LAS bf16x8*)(lds + PG8_SA(b, h) + aoff + m * 2048 + k * 1024); } while (0)
; #define PG8_LDB(dst, b, h) do { _Pragma("unroll") for (int n = 0; n < 2; ++n) _Pragma("unroll") for (int k = 0; k < 2; ++k) dst[n][k] = *(const PG8_LAS bf16x8*)(lds + PG8_SB(b, h) + boff + n * 2048 + k * 1024); } while (0)
; template <class Epi, class Sched, bool ALIGN_EPI = false, bool SP2 = false>
; __device__ __forceinline__ void gemm_phase(PG8_LAS unsigned char* lds, const Gemm g, const Sched& S, const Epi& E) {
;     ...
;         for (int t = 0; t < nt; t += 2) {
;             const bool last = (t == nt - 2);
;             const char* a1 = cA + (size_t)(t + 1) * kstep;
;             const char* a2 = last ? nA : cA + (size_t)(t + 2) * kstep; const char* b2 = last ? nB : cB + (size_t)(t + 2) * kstep;
;             const char* a3 = a2 + kstep; const char* b3 = b2 + kstep;
;             if (last && has_next) S.a_ready(nxt);
;             if constexpr (SP2) {
;             PG8_LDB(B0, 0, 0); PG8_LDB(B1, 0, 1); PG8_SCHED; PG8_LDA(At, 0, 0); PG8_STAGE(PG8_SA(1, 1), a1 + hstep, voffA);
;             PG8_WAIT_V(8); PG8_WAIT_L(0); PG8_BAR; PG8_MMA(0, 0, At, B0); PG8_MMA(0, 1, At, B1); PG8_BAR; PG8_SCHED;
;             PG8_LDA(At, 0, 1); PG8_STAGE(PG8_SB(0, 0), b2, voffB); PG8_STAGE(PG8_SB(0, 1), b2 + hstep, voffB); PG8_STAGE(PG8_SA(0, 0), a2, voffA);
;             PG8_WAIT_V(8); PG8_WAIT_L(0); PG8_BAR; PG8_MMA(1, 0, At, B0); PG8_MMA(1, 1, At, B1); PG8_BAR; PG8_SCHED;
;             PG8_LDB(B0, 1, 0); PG8_LDB(B1, 1, 1); PG8_SCHED; PG8_LDA(At, 1, 0); PG8_STAGE(PG8_SA(0, 1), a2 + hstep, voffA);
;             PG8_WAIT_V(8); PG8_WAIT_L(0); PG8_BAR; PG8_MMA(0, 0, At, B0); PG8_MMA(0, 1, At, B1); PG8_BAR; PG8_SCHED;
;             PG8_LDA(At, 1, 1); PG8_STAGE(PG8_SB(1, 0), b3, voffB); PG8_STAGE(PG8_SB(1, 1), b3 + hstep, voffB); PG8_STAGE(PG8_SA(1, 0), a3, voffA);
;             PG8_WAIT_V(8); PG8_WAIT_L(0); PG8_BAR; PG8_MMA(1, 0, At, B0); PG8_MMA(1, 1, At, B1); PG8_BAR; PG8_SCHED;
	s_add_i32 s14, s43, s23
	v_lshl_add_u64 v[178:179], v[178:179], 0, s[94:95]
	s_mov_b32 m0, s14
	ds_read_b128 v[210:213], v201 offset:49152
	ds_read_b128 v[214:217], v201 offset:50176
	ds_read_b128 v[218:221], v201 offset:51200
	ds_read_b128 v[222:225], v201 offset:52224
	ds_read_b128 v[226:229], v201 offset:53248
	ds_read_b128 v[230:233], v201 offset:54272
	ds_read_b128 v[234:237], v201 offset:55296
	ds_read_b128 v[238:241], v201 offset:56320
	global_load_lds_dwordx4 v[178:179], off
	v_lshl_add_u64 v[178:179], v[242:243], 0, s[94:95]
	s_add_i32 m0, s14, 0x2000
	s_add_i32 s14, s75, s23
	global_load_lds_dwordx4 v[178:179], off
	v_lshl_add_u64 v[178:179], v[244:245], 0, s[94:95]
	s_mov_b32 m0, s14
	s_nop 0
	global_load_lds_dwordx4 v[178:179], off
	v_lshl_add_u64 v[178:179], v[246:247], 0, s[94:95]
	s_add_i32 m0, s14, 0x2000
	s_nop 0
	global_load_lds_dwordx4 v[178:179], off
	v_lshl_add_u64 v[178:179], v[248:249], 0, s[94:95]
	s_mov_b32 m0, s63
	s_nop 0
	global_load_lds_dwordx4 v[178:179], off
	v_lshl_add_u64 v[178:179], v[250:251], 0, s[94:95]
	s_mov_b32 m0, s70
	s_nop 0
	global_load_lds_dwordx4 v[178:179], off
	s_waitcnt vmcnt(8)
	s_waitcnt lgkmcnt(0)
	s_barrier
	v_mfma_f32_16x16x32_bf16 v[62:65], v[130:133], v[210:213], v[62:65]
	v_mfma_f32_16x16x32_bf16 v[62:65], v[134:137], v[214:217], v[62:65]
	v_mfma_f32_16x16x32_bf16 v[58:61], v[138:141], v[210:213], v[58:61]
	v_mfma_f32_16x16x32_bf16 v[58:61], v[142:145], v[214:217], v[58:61]
	v_mfma_f32_16x16x32_bf16 v[46:49], v[130:133], v[218:221], v[46:49]
	v_mfma_f32_16x16x32_bf16 v[46:49], v[134:137], v[222:225], v[46:49]
	v_mfma_f32_16x16x32_bf16 v[42:45], v[138:141], v[218:221], v[42:45]
	v_mfma_f32_16x16x32_bf16 v[42:45], v[142:145], v[222:225], v[42:45]
	v_mfma_f32_16x16x32_bf16 v[30:33], v[130:133], v[226:229], v[30:33]
	v_mfma_f32_16x16x32_bf16 v[30:33], v[134:137], v[230:233], v[30:33]
	v_mfma_f32_16x16x32_bf16 v[26:29], v[138:141], v[226:229], v[26:29]
	v_mfma_f32_16x16x32_bf16 v[26:29], v[142:145], v[230:233], v[26:29]
	v_mfma_f32_16x16x32_bf16 v[14:17], v[130:133], v[234:237], v[14:17]
	v_mfma_f32_16x16x32_bf16 v[14:17], v[134:137], v[238:241], v[14:17]
	v_mfma_f32_16x16x32_bf16 v[10:13], v[138:141], v[234:237], v[10:13]
	v_mfma_f32_16x16x32_bf16 v[10:13], v[142:145], v[238:241], v[10:13]
	v_mfma_f32_16x16x32_bf16 v[54:57], v[170:173], v[210:213], v[54:57]
	v_mfma_f32_16x16x32_bf16 v[54:57], v[174:177], v[214:217], v[54:57]
	v_mfma_f32_16x16x32_bf16 v[50:53], v[202:205], v[210:213], v[50:53]
	v_mfma_f32_16x16x32_bf16 v[50:53], v[206:209], v[214:217], v[50:53]
	v_mfma_f32_16x16x32_bf16 v[38:41], v[170:173], v[218:221], v[38:41]
	v_mfma_f32_16x16x32_bf16 v[38:41], v[174:177], v[222:225], v[38:41]
	v_mfma_f32_16x16x32_bf16 v[34:37], v[202:205], v[218:221], v[34:37]
	v_mfma_f32_16x16x32_bf16 v[34:37], v[206:209], v[222:225], v[34:37]
	v_mfma_f32_16x16x32_bf16 v[22:25], v[170:173], v[226:229], v[22:25]
	v_mfma_f32_16x16x32_bf16 v[22:25], v[174:177], v[230:233], v[22:25]
	v_mfma_f32_16x16x32_bf16 v[18:21], v[202:205], v[226:229], v[18:21]
	v_mfma_f32_16x16x32_bf16 v[18:21], v[206:209], v[230:233], v[18:21]
	v_mfma_f32_16x16x32_bf16 v[6:9], v[170:173], v[234:237], v[6:9]
	v_mfma_f32_16x16x32_bf16 v[6:9], v[174:177], v[238:241], v[6:9]
	v_mfma_f32_16x16x32_bf16 v[2:5], v[202:205], v[234:237], v[2:5]
	v_mfma_f32_16x16x32_bf16 v[2:5], v[206:209], v[238:241], v[2:5]
	s_barrier
	s_add_u32 s12, s12, 0x100
	s_addc_u32 s13, s13, 0
	s_add_u32 s16, s16, 0x100
	s_addc_u32 s17, s17, 0
	s_cmp_ge_u32 s42, s28
	s_mov_b32 s14, s42
	s_cbranch_scc0 .LBB0_322
	s_branch .Lk_done
.LBB0_322:
	s_add_i32 s42, s14, 2
	s_add_u32 s43, s12, 0x80
	s_addc_u32 s15, s13, 0
	s_add_i32 s75, 0, 0x10000
	s_cmp_eq_u32 s25, s14
	s_cselect_b32 s15, s55, s15
	s_cselect_b32 s14, s54, s43
	s_cselect_b32 vcc_hi, s65, s17
	s_cselect_b32 vcc_lo, s64, s16
	s_add_i32 s43, 0, 0x14000
	v_add_u32_e32 v142, s75, v199
	v_add_u32_e32 v178, s43, v199
	ds_read_b128 v[130:133], v142
	ds_read_b128 v[134:137], v142 offset:1024
	ds_read_b128 v[138:141], v142 offset:2048
	ds_read_b128 v[142:145], v142 offset:3072
	ds_read_b128 v[170:173], v178
	ds_read_b128 v[174:177], v178 offset:1024
	ds_read_b128 v[202:205], v178 offset:2048
	ds_read_b128 v[206:209], v178 offset:3072
	v_lshl_add_u64 v[178:179], s[12:13], 0, v[166:167]
	s_add_i32 m0, s56, 0xc000
	ds_read_b128 v[210:213], v201
	ds_read_b128 v[214:217], v201 offset:1024
	ds_read_b128 v[218:221], v201 offset:2048
	ds_read_b128 v[222:225], v201 offset:3072
	ds_read_b128 v[226:229], v201 offset:4096
	ds_read_b128 v[230:233], v201 offset:5120
	ds_read_b128 v[234:237], v201 offset:6144
	ds_read_b128 v[238:241], v201 offset:7168
	global_load_lds_dwordx4 v[178:179], off
	v_lshl_add_u64 v[178:179], s[12:13], 0, v[168:169]
	s_add_i32 m0, s56, 0xe000
	s_nop 0
	global_load_lds_dwordx4 v[178:179], off
	s_waitcnt vmcnt(8)
	s_waitcnt lgkmcnt(0)
	s_barrier
; #define PG8_STAGE(bufoff, gbase, voff) do { _Pragma("unroll") for (int _i = 0; _i < 2; ++_i) \
;         __builtin_amdgcn_global_load_lds((const unsigned*)((const char*)(gbase) + (voff)[_i]), (PG8_LAS unsigned*)(lds + (bufoff) + ldsw + _i * 8192), 16, 0, 0); } while (0)
; #define PG8_LDA(dst, b, h) do { _Pragma("unroll") for (int m = 0; m < 4; ++m) _Pragma("unroll") for (int k = 0; k < 2; ++k) dst[m][k] = *(const PG8_LAS bf16x8*)(lds + PG8_SA(b, h) + aoff + m * 2048 + k * 1024); } while (0)
; #define PG8_MMA(ai, bj, At, Bt) do { __builtin_amdgcn_s_setprio(1); _Pragma("unroll") for (int m = 0; m < 4; ++m) _Pragma("unroll") for (int n = 0; n < 2; ++n) _Pragma("unroll") for (int k = 0; k < 2; ++k) \
;         acc[ai][bj][m][n] = __builtin_amdgcn_mfma_f32_16x16x32_bf16(Bt[n][k], At[m][k], acc[ai][bj][m][n], 0, 0, 0); __builtin_amdgcn_s_setprio(0); } while (0)
; #define PG8_WAIT_V(n) asm volatile("s_waitcnt vmcnt(" #n ")" ::: "memory")
; #define PG8_WAIT_L(n) asm volatile("s_waitcnt lgkmcnt(" #n ")" ::: "memory")
; #define PG8_BAR __builtin_amdgcn_s_barrier()
; #define PG8_SCHED __builtin_amdgcn_sched_barrier(0)
; template <class Epi, class Sched, bool ALIGN_EPI = false, bool SP2 = false>
; __device__ __forceinline__ void gemm_phase(PG8_LAS unsigned char* lds, const Gemm g, const Sched& S, const Epi& E) {
;     ...
;             PG8_WAIT_V(8); PG8_WAIT_L(0); PG8_BAR; PG8_MMA(0, 0, At, B0); PG8_MMA(0, 1, At, B1); PG8_BAR; PG8_SCHED;
;             PG8_LDA(At, 0, 1); PG8_STAGE(PG8_SB(0, 0), b2, voffB); PG8_STAGE(PG8_SB(0, 1), b2 + hstep, voffB); PG8_STAGE(PG8_SA(0, 0), a2, voffA);
;             PG8_WAIT_V(8); PG8_WAIT_L(0); PG8_BAR; PG8_MMA(1, 0, At, B0); PG8_MMA(1, 1, At, B1); PG8_BAR; PG8_SCHED;
	v_mfma_f32_16x16x32_bf16 v[126:129], v[130:133], v[210:213], v[126:129]
	v_mfma_f32_16x16x32_bf16 v[126:129], v[134:137], v[214:217], v[126:129]
	v_mfma_f32_16x16x32_bf16 v[122:125], v[138:141], v[210:213], v[122:125]
	v_mfma_f32_16x16x32_bf16 v[122:125], v[142:145], v[214:217], v[122:125]
	v_mfma_f32_16x16x32_bf16 v[110:113], v[130:133], v[218:221], v[110:113]
	v_mfma_f32_16x16x32_bf16 v[110:113], v[134:137], v[222:225], v[110:113]
	v_mfma_f32_16x16x32_bf16 v[106:109], v[138:141], v[218:221], v[106:109]
	v_mfma_f32_16x16x32_bf16 v[106:109], v[142:145], v[222:225], v[106:109]
	v_mfma_f32_16x16x32_bf16 v[94:97], v[130:133], v[226:229], v[94:97]
	v_mfma_f32_16x16x32_bf16 v[94:97], v[134:137], v[230:233], v[94:97]
	v_mfma_f32_16x16x32_bf16 v[90:93], v[138:141], v[226:229], v[90:93]
	v_mfma_f32_16x16x32_bf16 v[90:93], v[142:145], v[230:233], v[90:93]
	v_mfma_f32_16x16x32_bf16 v[78:81], v[130:133], v[234:237], v[78:81]
	v_mfma_f32_16x16x32_bf16 v[78:81], v[134:137], v[238:241], v[78:81]
	v_mfma_f32_16x16x32_bf16 v[74:77], v[138:141], v[234:237], v[74:77]
	v_mfma_f32_16x16x32_bf16 v[74:77], v[142:145], v[238:241], v[74:77]
	v_mfma_f32_16x16x32_bf16 v[118:121], v[170:173], v[210:213], v[118:121]
	v_mfma_f32_16x16x32_bf16 v[118:121], v[174:177], v[214:217], v[118:121]
	v_mfma_f32_16x16x32_bf16 v[114:117], v[202:205], v[210:213], v[114:117]
	v_mfma_f32_16x16x32_bf16 v[114:117], v[206:209], v[214:217], v[114:117]
	v_mfma_f32_16x16x32_bf16 v[102:105], v[170:173], v[218:221], v[102:105]
	v_mfma_f32_16x16x32_bf16 v[102:105], v[174:177], v[222:225], v[102:105]
	v_mfma_f32_16x16x32_bf16 v[98:101], v[202:205], v[218:221], v[98:101]
	v_mfma_f32_16x16x32_bf16 v[98:101], v[206:209], v[222:225], v[98:101]
	v_mfma_f32_16x16x32_bf16 v[86:89], v[170:173], v[226:229], v[86:89]
	v_mfma_f32_16x16x32_bf16 v[86:89], v[174:177], v[230:233], v[86:89]
	v_mfma_f32_16x16x32_bf16 v[82:85], v[202:205], v[226:229], v[82:85]
	v_mfma_f32_16x16x32_bf16 v[82:85], v[206:209], v[230:233], v[82:85]
	v_mfma_f32_16x16x32_bf16 v[70:73], v[170:173], v[234:237], v[70:73]
	v_mfma_f32_16x16x32_bf16 v[70:73], v[174:177], v[238:241], v[70:73]
	v_mfma_f32_16x16x32_bf16 v[66:69], v[202:205], v[234:237], v[66:69]
	v_mfma_f32_16x16x32_bf16 v[66:69], v[206:209], v[238:241], v[66:69]
	s_barrier
	s_add_i32 s75, s75, s23
	v_lshl_add_u64 v[178:179], vcc, 0, v[0:1]
	s_mov_b32 m0, s75
	ds_read_b128 v[210:213], v201 offset:16384
	ds_read_b128 v[214:217], v201 offset:17408
	ds_read_b128 v[218:221], v201 offset:18432
	ds_read_b128 v[222:225], v201 offset:19456
	ds_read_b128 v[226:229], v201 offset:20480
	ds_read_b128 v[230:233], v201 offset:21504
	ds_read_b128 v[234:237], v201 offset:22528
	ds_read_b128 v[238:241], v201 offset:23552
	global_load_lds_dwordx4 v[178:179], off
	s_add_i32 m0, s75, 0x2000
	v_lshl_add_u64 v[242:243], vcc, 0, v[162:163]
	s_add_u32 vcc_lo, vcc_lo, s84
	s_addc_u32 vcc_hi, vcc_hi, 0
	s_add_i32 s43, s43, s23
	global_load_lds_dwordx4 v[242:243], off
	v_lshl_add_u64 v[244:245], vcc, 0, v[0:1]
	s_mov_b32 m0, s43
	v_lshl_add_u64 v[246:247], vcc, 0, v[162:163]
	global_load_lds_dwordx4 v[244:245], off
	s_add_i32 m0, s43, 0x2000
	v_lshl_add_u64 v[248:249], s[14:15], 0, v[158:159]
	global_load_lds_dwordx4 v[246:247], off
	s_mov_b32 m0, s56
	v_lshl_add_u64 v[250:251], s[14:15], 0, v[160:161]
	global_load_lds_dwordx4 v[248:249], off
	s_mov_b32 m0, s82
	s_nop 0
	global_load_lds_dwordx4 v[250:251], off
	s_waitcnt vmcnt(8)
	s_waitcnt lgkmcnt(0)
	s_barrier
	v_mfma_f32_16x16x32_bf16 v[62:65], v[130:133], v[210:213], v[62:65]
	v_mfma_f32_16x16x32_bf16 v[62:65], v[134:137], v[214:217], v[62:65]
	v_mfma_f32_16x16x32_bf16 v[58:61], v[138:141], v[210:213], v[58:61]
	v_mfma_f32_16x16x32_bf16 v[58:61], v[142:145], v[214:217], v[58:61]
	v_mfma_f32_16x16x32_bf16 v[46:49], v[130:133], v[218:221], v[46:49]
	v_mfma_f32_16x16x32_bf16 v[46:49], v[134:137], v[222:225], v[46:49]
	v_mfma_f32_16x16x32_bf16 v[42:45], v[138:141], v[218:221], v[42:45]
	v_mfma_f32_16x16x32_bf16 v[42:45], v[142:145], v[222:225], v[42:45]
	v_mfma_f32_16x16x32_bf16 v[30:33], v[130:133], v[226:229], v[30:33]
	v_mfma_f32_16x16x32_bf16 v[30:33], v[134:137], v[230:233], v[30:33]
	v_mfma_f32_16x16x32_bf16 v[26:29], v[138:141], v[226:229], v[26:29]
	v_mfma_f32_16x16x32_bf16 v[26:29], v[142:145], v[230:233], v[26:29]
	v_mfma_f32_16x16x32_bf16 v[14:17], v[130:133], v[234:237], v[14:17]
	v_mfma_f32_16x16x32_bf16 v[14:17], v[134:137], v[238:241], v[14:17]
	v_mfma_f32_16x16x32_bf16 v[10:13], v[138:141], v[234:237], v[10:13]
	v_mfma_f32_16x16x32_bf16 v[10:13], v[142:145], v[238:241], v[10:13]
	v_mfma_f32_16x16x32_bf16 v[54:57], v[170:173], v[210:213], v[54:57]
	v_mfma_f32_16x16x32_bf16 v[54:57], v[174:177], v[214:217], v[54:57]
	v_mfma_f32_16x16x32_bf16 v[50:53], v[202:205], v[210:213], v[50:53]
	v_mfma_f32_16x16x32_bf16 v[50:53], v[206:209], v[214:217], v[50:53]
	v_mfma_f32_16x16x32_bf16 v[38:41], v[170:173], v[218:221], v[38:41]
	v_mfma_f32_16x16x32_bf16 v[38:41], v[174:177], v[222:225], v[38:41]
	v_mfma_f32_16x16x32_bf16 v[34:37], v[202:205], v[218:221], v[34:37]
	v_mfma_f32_16x16x32_bf16 v[34:37], v[206:209], v[222:225], v[34:37]
	v_mfma_f32_16x16x32_bf16 v[22:25], v[170:173], v[226:229], v[22:25]
	v_mfma_f32_16x16x32_bf16 v[22:25], v[174:177], v[230:233], v[22:25]
	v_mfma_f32_16x16x32_bf16 v[18:21], v[202:205], v[226:229], v[18:21]
	v_mfma_f32_16x16x32_bf16 v[18:21], v[206:209], v[230:233], v[18:21]
	v_mfma_f32_16x16x32_bf16 v[6:9], v[170:173], v[234:237], v[6:9]
	v_mfma_f32_16x16x32_bf16 v[6:9], v[174:177], v[238:241], v[6:9]
	v_mfma_f32_16x16x32_bf16 v[2:5], v[202:205], v[234:237], v[2:5]
	v_mfma_f32_16x16x32_bf16 v[2:5], v[206:209], v[238:241], v[2:5]
	s_barrier
; #define PG8_STAGE(bufoff, gbase, voff) do { _Pragma("unroll") for (int _i = 0; _i < 2; ++_i) \
;         __builtin_amdgcn_global_load_lds((const unsigned*)((const char*)(gbase) + (voff)[_i]), (PG8_LAS unsigned*)(lds + (bufoff) + ldsw + _i * 8192), 16, 0, 0); } while (0)
; #define PG8_LDA(dst, b, h) do { _Pragma("unroll") for (int m = 0; m < 4; ++m) _Pragma("unroll") for (int k = 0; k < 2; ++k) dst[m][k] = *(const PG8_LAS bf16x8*)(lds + PG8_SA(b, h) + aoff + m * 2048 + k * 1024); } while (0)
; #define PG8_LDB(dst, b, h) do { _Pragma("unroll") for (int n = 0; n < 2; ++n) _Pragma("unroll") for (int k = 0; k < 2; ++k) dst[n][k] = *(const PG8_LAS bf16x8*)(lds + PG8_SB(b, h) + boff + n * 2048 + k * 1024); } while (0)
; #define PG8_MMA(ai, bj, At, Bt) do { __builtin_amdgcn_s_setprio(1); _Pragma("unroll") for (int m = 0; m < 4; ++m) _Pragma("unroll") for (int n = 0; n < 2; ++n) _Pragma("unroll") for (int k = 0; k < 2; ++k) \
;         acc[ai][bj][m][n] = __builtin_amdgcn_mfma_f32_16x16x32_bf16(Bt[n][k], At[m][k], acc[ai][bj][m][n], 0, 0, 0); __builtin_amdgcn_s_setprio(0); } while (0)
; #define PG8_WAIT_V(n) asm volatile("s_waitcnt vmcnt(" #n ")" ::: "memory")
; #define PG8_WAIT_L(n) asm volatile("s_waitcnt lgkmcnt(" #n ")" ::: "memory")
; #define PG8_BAR __builtin_amdgcn_s_barrier()
; #define PG8_SCHED __builtin_amdgcn_sched_barrier(0)
; template <class Epi, class Sched, bool ALIGN_EPI = false, bool SP2 = false>
; __device__ __forceinline__ void gemm_phase(PG8_LAS unsigned char* lds, const Gemm g, const Sched& S, const Epi& E) {
;     ...
;             PG8_LDB(B0, 1, 0); PG8_LDB(B1, 1, 1); PG8_SCHED; PG8_LDA(At, 1, 0); PG8_STAGE(PG8_SA(0, 1), a2 + hstep, voffA);
;             PG8_WAIT_V(8); PG8_WAIT_L(0); PG8_BAR; PG8_MMA(0, 0, At, B0); PG8_MMA(0, 1, At, B1); PG8_BAR; PG8_SCHED;
;             PG8_LDA(At, 1, 1); PG8_STAGE(PG8_SB(1, 0), b3, voffB); PG8_STAGE(PG8_SB(1, 1), b3 + hstep, voffB); PG8_STAGE(PG8_SA(1, 0), a3, voffA);
;             PG8_WAIT_V(8); PG8_WAIT_L(0); PG8_BAR; PG8_MMA(1, 0, At, B0); PG8_MMA(1, 1, At, B1); PG8_BAR; PG8_SCHED;
	s_add_i32 s43, 0, 0x18000
	s_add_i32 s75, 0, 0x1c000
	v_add_u32_e32 v142, s43, v199
	v_add_u32_e32 v206, s75, v199
	ds_read_b128 v[130:133], v142
	ds_read_b128 v[134:137], v142 offset:1024
	ds_read_b128 v[138:141], v142 offset:2048
	ds_read_b128 v[142:145], v142 offset:3072
	ds_read_b128 v[170:173], v206
	ds_read_b128 v[174:177], v206 offset:1024
	ds_read_b128 v[202:205], v206 offset:2048
	ds_read_b128 v[206:209], v206 offset:3072
	s_add_u32 s14, s14, s84
	s_addc_u32 s15, s15, 0
	s_mov_b32 m0, s83
	v_lshl_add_u64 v[252:253], s[14:15], 0, v[158:159]
	ds_read_b128 v[210:213], v201 offset:32768
	ds_read_b128 v[214:217], v201 offset:33792
	ds_read_b128 v[218:221], v201 offset:34816
	ds_read_b128 v[222:225], v201 offset:35840
	ds_read_b128 v[226:229], v201 offset:36864
	ds_read_b128 v[230:233], v201 offset:37888
	ds_read_b128 v[234:237], v201 offset:38912
	ds_read_b128 v[238:241], v201 offset:39936
	global_load_lds_dwordx4 v[252:253], off
	v_lshl_add_u64 v[252:253], s[14:15], 0, v[160:161]
	s_mov_b32 m0, s24
	s_nop 0
	global_load_lds_dwordx4 v[252:253], off
	s_waitcnt vmcnt(8)
	s_waitcnt lgkmcnt(0)
	s_barrier
	v_mfma_f32_16x16x32_bf16 v[126:129], v[130:133], v[210:213], v[126:129]
	v_mfma_f32_16x16x32_bf16 v[126:129], v[134:137], v[214:217], v[126:129]
	v_mfma_f32_16x16x32_bf16 v[122:125], v[138:141], v[210:213], v[122:125]
	v_mfma_f32_16x16x32_bf16 v[122:125], v[142:145], v[214:217], v[122:125]
	v_mfma_f32_16x16x32_bf16 v[110:113], v[130:133], v[218:221], v[110:113]
	v_mfma_f32_16x16x32_bf16 v[110:113], v[134:137], v[222:225], v[110:113]
	v_mfma_f32_16x16x32_bf16 v[106:109], v[138:141], v[218:221], v[106:109]
	v_mfma_f32_16x16x32_bf16 v[106:109], v[142:145], v[222:225], v[106:109]
	v_mfma_f32_16x16x32_bf16 v[94:97], v[130:133], v[226:229], v[94:97]
	v_mfma_f32_16x16x32_bf16 v[94:97], v[134:137], v[230:233], v[94:97]
	v_mfma_f32_16x16x32_bf16 v[90:93], v[138:141], v[226:229], v[90:93]
	v_mfma_f32_16x16x32_bf16 v[90:93], v[142:145], v[230:233], v[90:93]
	v_mfma_f32_16x16x32_bf16 v[78:81], v[130:133], v[234:237], v[78:81]
	v_mfma_f32_16x16x32_bf16 v[78:81], v[134:137], v[238:241], v[78:81]
	v_mfma_f32_16x16x32_bf16 v[74:77], v[138:141], v[234:237], v[74:77]
	v_mfma_f32_16x16x32_bf16 v[74:77], v[142:145], v[238:241], v[74:77]
	v_mfma_f32_16x16x32_bf16 v[118:121], v[170:173], v[210:213], v[118:121]
	v_mfma_f32_16x16x32_bf16 v[118:121], v[174:177], v[214:217], v[118:121]
	v_mfma_f32_16x16x32_bf16 v[114:117], v[202:205], v[210:213], v[114:117]
	v_mfma_f32_16x16x32_bf16 v[114:117], v[206:209], v[214:217], v[114:117]
	v_mfma_f32_16x16x32_bf16 v[102:105], v[170:173], v[218:221], v[102:105]
	v_mfma_f32_16x16x32_bf16 v[102:105], v[174:177], v[222:225], v[102:105]
	v_mfma_f32_16x16x32_bf16 v[98:101], v[202:205], v[218:221], v[98:101]
	v_mfma_f32_16x16x32_bf16 v[98:101], v[206:209], v[222:225], v[98:101]
	v_mfma_f32_16x16x32_bf16 v[86:89], v[170:173], v[226:229], v[86:89]
	v_mfma_f32_16x16x32_bf16 v[86:89], v[174:177], v[230:233], v[86:89]
	v_mfma_f32_16x16x32_bf16 v[82:85], v[202:205], v[226:229], v[82:85]
	v_mfma_f32_16x16x32_bf16 v[82:85], v[206:209], v[230:233], v[82:85]
	v_mfma_f32_16x16x32_bf16 v[70:73], v[170:173], v[234:237], v[70:73]
	v_mfma_f32_16x16x32_bf16 v[70:73], v[174:177], v[238:241], v[70:73]
	v_mfma_f32_16x16x32_bf16 v[66:69], v[202:205], v[234:237], v[66:69]
	v_mfma_f32_16x16x32_bf16 v[66:69], v[206:209], v[238:241], v[66:69]
	s_barrier
	s_add_i32 s14, s43, s23
	v_lshl_add_u64 v[178:179], v[178:179], 0, s[94:95]
	s_mov_b32 m0, s14
	ds_read_b128 v[210:213], v201 offset:49152
	ds_read_b128 v[214:217], v201 offset:50176
	ds_read_b128 v[218:221], v201 offset:51200
	ds_read_b128 v[222:225], v201 offset:52224
	ds_read_b128 v[226:229], v201 offset:53248
	ds_read_b128 v[230:233], v201 offset:54272
	ds_read_b128 v[234:237], v201 offset:55296
	ds_read_b128 v[238:241], v201 offset:56320
	global_load_lds_dwordx4 v[178:179], off
	v_lshl_add_u64 v[178:179], v[242:243], 0, s[94:95]
	s_add_i32 m0, s14, 0x2000
	s_add_i32 s14, s75, s23
	global_load_lds_dwordx4 v[178:179], off
	v_lshl_add_u64 v[178:179], v[244:245], 0, s[94:95]
	s_mov_b32 m0, s14
	s_nop 0
	global_load_lds_dwordx4 v[178:179], off
	v_lshl_add_u64 v[178:179], v[246:247], 0, s[94:95]
	s_add_i32 m0, s14, 0x2000
	s_nop 0
	global_load_lds_dwordx4 v[178:179], off
	v_lshl_add_u64 v[178:179], v[248:249], 0, s[94:95]
	s_mov_b32 m0, s63
	s_nop 0
	global_load_lds_dwordx4 v[178:179], off
	v_lshl_add_u64 v[178:179], v[250:251], 0, s[94:95]
	s_mov_b32 m0, s70
	s_nop 0
	global_load_lds_dwordx4 v[178:179], off
	s_waitcnt vmcnt(8)
	s_waitcnt lgkmcnt(0)
	s_barrier
	v_mfma_f32_16x16x32_bf16 v[62:65], v[130:133], v[210:213], v[62:65]
	v_mfma_f32_16x16x32_bf16 v[62:65], v[134:137], v[214:217], v[62:65]
	v_mfma_f32_16x16x32_bf16 v[58:61], v[138:141], v[210:213], v[58:61]
	v_mfma_f32_16x16x32_bf16 v[58:61], v[142:145], v[214:217], v[58:61]
	v_mfma_f32_16x16x32_bf16 v[46:49], v[130:133], v[218:221], v[46:49]
	v_mfma_f32_16x16x32_bf16 v[46:49], v[134:137], v[222:225], v[46:49]
	v_mfma_f32_16x16x32_bf16 v[42:45], v[138:141], v[218:221], v[42:45]
	v_mfma_f32_16x16x32_bf16 v[42:45], v[142:145], v[222:225], v[42:45]
	v_mfma_f32_16x16x32_bf16 v[30:33], v[130:133], v[226:229], v[30:33]
	v_mfma_f32_16x16x32_bf16 v[30:33], v[134:137], v[230:233], v[30:33]
	v_mfma_f32_16x16x32_bf16 v[26:29], v[138:141], v[226:229], v[26:29]
	v_mfma_f32_16x16x32_bf16 v[26:29], v[142:145], v[230:233], v[26:29]
	v_mfma_f32_16x16x32_bf16 v[14:17], v[130:133], v[234:237], v[14:17]
	v_mfma_f32_16x16x32_bf16 v[14:17], v[134:137], v[238:241], v[14:17]
	v_mfma_f32_16x16x32_bf16 v[10:13], v[138:141], v[234:237], v[10:13]
	v_mfma_f32_16x16x32_bf16 v[10:13], v[142:145], v[238:241], v[10:13]
	v_mfma_f32_16x16x32_bf16 v[54:57], v[170:173], v[210:213], v[54:57]
	v_mfma_f32_16x16x32_bf16 v[54:57], v[174:177], v[214:217], v[54:57]
	v_mfma_f32_16x16x32_bf16 v[50:53], v[202:205], v[210:213], v[50:53]
	v_mfma_f32_16x16x32_bf16 v[50:53], v[206:209], v[214:217], v[50:53]
	v_mfma_f32_16x16x32_bf16 v[38:41], v[170:173], v[218:221], v[38:41]
	v_mfma_f32_16x16x32_bf16 v[38:41], v[174:177], v[222:225], v[38:41]
	v_mfma_f32_16x16x32_bf16 v[34:37], v[202:205], v[218:221], v[34:37]
	v_mfma_f32_16x16x32_bf16 v[34:37], v[206:209], v[222:225], v[34:37]
	v_mfma_f32_16x16x32_bf16 v[22:25], v[170:173], v[226:229], v[22:25]
	v_mfma_f32_16x16x32_bf16 v[22:25], v[174:177], v[230:233], v[22:25]
	v_mfma_f32_16x16x32_bf16 v[18:21], v[202:205], v[226:229], v[18:21]
	v_mfma_f32_16x16x32_bf16 v[18:21], v[206:209], v[230:233], v[18:21]
	v_mfma_f32_16x16x32_bf16 v[6:9], v[170:173], v[234:237], v[6:9]
	v_mfma_f32_16x16x32_bf16 v[6:9], v[174:177], v[238:241], v[6:9]
	v_mfma_f32_16x16x32_bf16 v[2:5], v[202:205], v[234:237], v[2:5]
	v_mfma_f32_16x16x32_bf16 v[2:5], v[206:209], v[238:241], v[2:5]
	s_barrier
	s_add_u32 s12, s12, 0x100
	s_addc_u32 s13, s13, 0
	s_add_u32 s16, s16, 0x100
	s_addc_u32 s17, s17, 0
	s_cmp_ge_u32 s42, s28
	s_mov_b32 s14, s42
	s_cbranch_scc0 .LBB0_322
